# lnffn (layer 1): first two expert rows of the next token row prefetched during the current row's LayerNorm
# speedup vs baseline: 1.0011x; 1.0011x over previous
.LBB0_1646:
	s_cmp_lt_i32 s90, 19
	s_cselect_b64 s[0:1], -1, 0
	s_cmp_gt_i32 s91, 18
	s_cselect_b64 s[4:5], -1, 0
	s_and_b64 s[0:1], s[0:1], s[4:5]
	s_andn2_b64 vcc, exec, s[0:1]
	s_cbranch_vccnz .LBB0_1710
	s_load_dword s13, s[96:97], 0x128
	s_add_u32 s4, s96, 0x128
	v_ashrrev_i32_e32 v0, 6, v77
	s_waitcnt vmcnt(0)
	v_lshl_add_u32 v8, s2, 3, v0
	s_movk_i32 s18, 0x4000
	s_addc_u32 s5, s97, 0
	v_cmp_gt_i32_e32 vcc, s18, v8
	s_waitcnt lgkmcnt(0)
	s_and_saveexec_b64 s[2:3], vcc
	s_cbranch_execz .LBB0_1656
	v_readlane_b32 s20, v126, 2
	v_readlane_b32 s21, v126, 3
	v_readlane_b32 s22, v126, 4
	v_readlane_b32 s23, v126, 5
	v_readlane_b32 s24, v126, 6
	v_readlane_b32 s25, v126, 7
	v_readlane_b32 s26, v126, 8
	v_readlane_b32 s27, v126, 9
	s_mov_b64 s[20:21], s[24:25]
	s_lshl_b32 s19, s13, 3
	s_mov_b64 s[22:23], s[26:27]
	s_add_u32 s6, s22, 0x1d3e8000
	s_addc_u32 s7, s23, 0
	s_add_u32 s0, s56, 0x1000
	s_addc_u32 s1, s57, 0
	s_add_u32 s8, s54, 0x1000
	s_addc_u32 s9, s55, 0
	s_add_u32 s10, s22, 0x190c8000
	v_ashrrev_i32_e32 v9, 31, v8
	s_addc_u32 s11, s23, 0
	v_and_b32_e32 v4, 15, v77
	v_lshlrev_b64 v[0:1], 6, v[8:9]
	v_lshlrev_b32_e32 v6, 2, v77
	v_lshl_add_u64 v[2:3], s[10:11], 0, v[0:1]
	v_lshlrev_b32_e32 v0, 2, v4
	v_mov_b32_e32 v1, 0
	v_lshlrev_b64 v[4:5], 11, v[8:9]
	v_and_b32_e32 v28, 0xfc, v6
	v_lshl_add_u64 v[4:5], s[6:7], 0, v[4:5]
	v_lshlrev_b32_e32 v6, 1, v28
	v_mov_b32_e32 v7, v1
	v_lshl_add_u64 v[4:5], v[4:5], 0, v[6:7]
	v_lshl_add_u64 v[2:3], v[2:3], 0, v[0:1]
	global_load_dwordx2 v[42:43], v[4:5], off
	global_load_dwordx2 v[40:41], v[4:5], off offset:512
	global_load_dwordx2 v[38:39], v[4:5], off offset:1024
	global_load_dwordx2 v[36:37], v[4:5], off offset:1536
	global_load_dword v9, v[2:3], off
	v_lshl_add_u64 v[2:3], s[10:11], 0, v[0:1]
	v_mbcnt_lo_u32_b32 v0, -1, 0
	v_mbcnt_hi_u32_b32 v0, -1, v0
	v_and_b32_e32 v10, 64, v0
	v_add_u32_e32 v10, 64, v10
	v_xor_b32_e32 v11, 1, v0
	v_cmp_lt_i32_e32 vcc, v11, v10
	v_or_b32_e32 v30, 0x100, v28
	v_or_b32_e32 v32, 0x200, v28
	v_cndmask_b32_e32 v11, v0, v11, vcc
	v_lshlrev_b32_e32 v61, 2, v11
	v_xor_b32_e32 v11, 2, v0
	v_cmp_lt_i32_e32 vcc, v11, v10
	v_or_b32_e32 v34, 0x300, v28
	v_lshl_add_u64 v[4:5], s[6:7], 0, v[6:7]
	v_cndmask_b32_e32 v11, v0, v11, vcc
	v_lshlrev_b32_e32 v66, 2, v11
	v_xor_b32_e32 v11, 4, v0
	v_cmp_lt_i32_e32 vcc, v11, v10
	v_lshl_add_u64 v[6:7], s[22:23], 0, v[6:7]
	s_mov_b64 s[6:7], 0x333e8000
	v_cndmask_b32_e32 v11, v0, v11, vcc
	v_lshlrev_b32_e32 v67, 2, v11
	v_xor_b32_e32 v11, 8, v0
	v_cmp_lt_i32_e32 vcc, v11, v10
	v_lshlrev_b32_e32 v16, 2, v30
	v_mov_b32_e32 v17, v1
	v_cndmask_b32_e32 v11, v0, v11, vcc
	v_lshlrev_b32_e32 v68, 2, v11
	v_xor_b32_e32 v11, 16, v0
	v_cmp_lt_i32_e32 vcc, v11, v10
	v_lshlrev_b32_e32 v20, 2, v32
	v_mov_b32_e32 v21, v1
	v_cndmask_b32_e32 v11, v0, v11, vcc
	v_lshlrev_b32_e32 v69, 2, v11
	v_xor_b32_e32 v11, 32, v0
	v_cmp_lt_i32_e32 vcc, v11, v10
	v_lshlrev_b32_e32 v24, 2, v34
	v_mov_b32_e32 v25, v1
	v_cndmask_b32_e32 v0, v0, v11, vcc
	v_lshlrev_b32_e32 v70, 2, v0
	v_lshlrev_b32_e32 v0, 2, v28
	v_lshl_add_u64 v[6:7], v[6:7], 0, s[6:7]
	s_mov_b32 s7, 0
	v_lshl_add_u64 v[10:11], s[8:9], 0, v[0:1]
	v_lshl_add_u64 v[12:13], s[0:1], 0, v[0:1]
	v_lshl_add_u64 v[14:15], s[8:9], 0, v[16:17]
	v_lshl_add_u64 v[16:17], s[0:1], 0, v[16:17]
	v_lshl_add_u64 v[18:19], s[8:9], 0, v[20:21]
	v_lshl_add_u64 v[20:21], s[0:1], 0, v[20:21]
	v_lshl_add_u64 v[22:23], s[8:9], 0, v[24:25]
	v_lshl_add_u64 v[24:25], s[0:1], 0, v[24:25]
	v_lshl_add_u64 v[26:27], s[20:21], 0, v[0:1]
	s_mov_b64 s[8:9], 0
	s_movk_i32 s20, 0x3fff
	s_movk_i32 s21, 0x1fff
	s_movk_i32 s22, 0x6000
	s_mov_b64 s[10:11], 0x18e85000
	v_lshlrev_b32_e32 v0, 2, v28
	s_mov_b32 s12, 0x3fb504f3
	v_lshlrev_b32_e32 v28, 2, v30
	v_lshlrev_b32_e32 v30, 2, v32
	v_lshlrev_b32_e32 v32, 2, v34
	v_mov_b32_e32 v71, 0x358637bd
	s_mov_b32 s23, 0x800000
	s_waitcnt vmcnt(4)
	v_mov_b64_e32 v[72:73], v[42:43]
	s_waitcnt vmcnt(3)
	v_mov_b64_e32 v[74:75], v[40:41]
	s_waitcnt vmcnt(2)
	v_mov_b64_e32 v[76:77], v[38:39]
	s_waitcnt vmcnt(1)
	v_mov_b64_e32 v[78:79], v[36:37]
	s_waitcnt vmcnt(0)
	v_mov_b32_e32 v35, v9
	global_load_dwordx4 a[8:11], v[10:11], off
	global_load_dwordx4 a[12:15], v[12:13], off
	global_load_dwordx4 a[16:19], v[14:15], off
	global_load_dwordx4 a[20:23], v[16:17], off
	global_load_dwordx4 a[24:27], v[18:19], off
	global_load_dwordx4 a[28:31], v[20:21], off
	global_load_dwordx4 a[32:35], v[22:23], off
	global_load_dwordx4 a[36:39], v[24:25], off
	v_cmp_lt_i32_e64 s[40:41], -1, v9
	s_and_b32 s40, s40, 0xffff
	s_mov_b32 s41, 0
	s_ff1_i32_b64 s45, s[40:41]
	s_add_u32 s46, s40, -1
	s_addc_u32 s47, s41, -1
	s_cmp_lg_u64 s[40:41], 0
	s_cselect_b32 s43, 1, 0
	s_cselect_b32 s45, s45, 0
	s_cselect_b32 s46, s46, 0
	s_cselect_b32 s47, s47, 0
	s_and_b64 s[40:41], s[40:41], s[46:47]
	s_ff1_i32_b64 s48, s[40:41]
	s_add_u32 s46, s40, -1
	s_addc_u32 s47, s41, -1
	s_cmp_lg_u64 s[40:41], 0
	s_cselect_b32 s42, 1.0, 0
	s_cselect_b32 s48, s48, s45
	s_cselect_b32 s46, s46, 0
	s_cselect_b32 s47, s47, 0
	s_and_b64 s[40:41], s[40:41], s[46:47]
	v_readlane_b32 s49, v9, s45
	v_readlane_b32 s50, v9, s48
	s_max_i32 s49, s49, 0
	s_max_i32 s50, s50, 0
	s_lshl_b32 s45, s45, 11
	s_lshl_b32 s48, s48, 11
	s_add_i32 s45, s45, s49
	s_add_i32 s48, s48, s50
	s_lshl_b32 s46, s45, 11
	s_mov_b32 s47, 0
	s_lshl_b32 s50, s48, 11
	s_mov_b32 s51, 0
	v_lshl_add_u64 v[104:105], v[6:7], 0, s[46:47]
	v_lshl_add_u64 v[106:107], v[6:7], 0, s[50:51]
	global_load_dwordx2 v[108:109], v[104:105], off nt
	global_load_dwordx2 v[110:111], v[106:107], off nt
	global_load_dwordx2 v[112:113], v[104:105], off offset:512 nt
	global_load_dwordx2 v[114:115], v[106:107], off offset:512 nt
	global_load_dwordx2 v[116:117], v[104:105], off offset:1024 nt
	global_load_dwordx2 v[118:119], v[106:107], off offset:1024 nt
	global_load_dwordx2 v[120:121], v[104:105], off offset:1536 nt
	global_load_dwordx2 v[122:123], v[106:107], off offset:1536 nt
	s_waitcnt vmcnt(0)
	s_branch .LBB0_1651

.LBB0_1650:
	v_add_u32_e32 v9, 0xffffe000, v8
	v_lshrrev_b32_e32 v9, 11, v9
	v_readlane_b32 s24, v126, 2
	v_add_u32_e32 v9, 6, v9
	v_readlane_b32 s30, v126, 8
	v_readlane_b32 s31, v126, 9
	v_cndmask_b32_e64 v9, 5, v9, s[0:1]
	v_mov_b32_e32 v29, v1
	v_mov_b64_e32 v[62:63], s[30:31]
	v_mad_u64_u32 v[62:63], s[0:1], v9, s22, v[62:63]
	v_lshl_add_u64 v[88:89], v[62:63], 0, s[10:11]
	v_lshl_add_u64 v[62:63], v[88:89], 0, v[0:1]
	v_lshl_add_u64 v[80:81], v[88:89], 0, v[28:29]
	v_mov_b32_e32 v31, v1
	global_load_dwordx4 v[62:65], v[62:63], off
	s_nop 0
	global_load_dwordx4 v[80:83], v[80:81], off
	v_lshl_add_u64 v[84:85], v[88:89], 0, v[30:31]
	global_load_dwordx4 v[84:87], v[84:85], off
	v_mov_b32_e32 v33, v1
	v_lshl_add_u64 v[88:89], v[88:89], 0, v[32:33]
	global_load_dwordx4 v[88:91], v[88:89], off
	s_waitcnt vmcnt(4)
	v_cmp_lt_i32_e64 s[40:41], -1, v35
	s_and_b32 s40, s40, 0xffff
	s_mov_b32 s41, 0
	s_ff1_i32_b64 s45, s[40:41]
	s_add_u32 s46, s40, -1
	s_addc_u32 s47, s41, -1
	s_cmp_lg_u64 s[40:41], 0
	s_cselect_b32 s43, 1, 0
	s_cselect_b32 s45, s45, 0
	s_cselect_b32 s46, s46, 0
	s_cselect_b32 s47, s47, 0
	s_and_b64 s[40:41], s[40:41], s[46:47]
	s_ff1_i32_b64 s48, s[40:41]
	s_add_u32 s46, s40, -1
	s_addc_u32 s47, s41, -1
	s_cmp_lg_u64 s[40:41], 0
	s_cselect_b32 s42, 1.0, 0
	s_cselect_b32 s48, s48, s45
	s_cselect_b32 s46, s46, 0
	s_cselect_b32 s47, s47, 0
	s_and_b64 s[40:41], s[40:41], s[46:47]
	v_readlane_b32 s49, v35, s45
	v_readlane_b32 s50, v35, s48
	s_max_i32 s49, s49, 0
	s_max_i32 s50, s50, 0
	s_lshl_b32 s45, s45, 11
	s_lshl_b32 s48, s48, 11
	s_add_i32 s45, s45, s49
	s_add_i32 s48, s48, s50
	s_lshl_b32 s46, s45, 11
	s_mov_b32 s47, 0
	s_lshl_b32 s50, s48, 11
	s_mov_b32 s51, 0
	v_lshl_add_u64 v[104:105], v[6:7], 0, s[46:47]
	v_lshl_add_u64 v[106:107], v[6:7], 0, s[50:51]
	global_load_dwordx2 v[108:109], v[104:105], off nt
	global_load_dwordx2 v[110:111], v[106:107], off nt
	global_load_dwordx2 v[112:113], v[104:105], off offset:512 nt
	global_load_dwordx2 v[114:115], v[106:107], off offset:512 nt
	global_load_dwordx2 v[116:117], v[104:105], off offset:1024 nt
	global_load_dwordx2 v[118:119], v[106:107], off offset:1024 nt
	global_load_dwordx2 v[120:121], v[104:105], off offset:1536 nt
	global_load_dwordx2 v[122:123], v[106:107], off offset:1536 nt
	v_lshlrev_b32_e32 v92, 16, v42
	v_and_b32_e32 v93, 0xffff0000, v42
	v_lshlrev_b32_e32 v42, 16, v43
	v_and_b32_e32 v43, 0xffff0000, v43
	v_lshlrev_b32_e32 v94, 16, v40
	v_and_b32_e32 v95, 0xffff0000, v40
	v_lshlrev_b32_e32 v96, 16, v41
	v_and_b32_e32 v97, 0xffff0000, v41
	v_lshlrev_b32_e32 v100, 16, v36
	v_and_b32_e32 v101, 0xffff0000, v36
	v_lshlrev_b32_e32 v102, 16, v37
	v_and_b32_e32 v103, 0xffff0000, v37
	v_lshlrev_b32_e32 v98, 16, v38
	v_and_b32_e32 v99, 0xffff0000, v38
	v_lshlrev_b32_e32 v38, 16, v39
	v_and_b32_e32 v39, 0xffff0000, v39
	s_and_b64 s[14:15], exec, vcc
	s_or_b64 s[8:9], s[14:15], s[8:9]
	v_readlane_b32 s25, v126, 3
	v_readlane_b32 s26, v126, 4
	v_readlane_b32 s27, v126, 5
	v_readlane_b32 s28, v126, 6
	v_readlane_b32 s29, v126, 7
	s_waitcnt vmcnt(11)
	v_pk_mul_f32 v[36:37], v[58:59], v[64:65]
	v_pk_mul_f32 v[40:41], v[56:57], v[62:63]
	s_waitcnt vmcnt(10)
	v_pk_mul_f32 v[54:55], v[54:55], v[82:83]
	v_pk_mul_f32 v[52:53], v[52:53], v[80:81]
	s_waitcnt vmcnt(9)
	v_pk_mul_f32 v[56:57], v[50:51], v[86:87]
	v_pk_mul_f32 v[58:59], v[48:49], v[84:85]
	v_pk_fma_f32 v[48:49], v[92:93], s[12:13], v[40:41] op_sel_hi:[1,0,1]
	v_pk_fma_f32 v[50:51], v[42:43], s[12:13], v[36:37] op_sel_hi:[1,0,1]
	v_pk_fma_f32 v[40:41], v[94:95], s[12:13], v[52:53] op_sel_hi:[1,0,1]
	v_pk_fma_f32 v[42:43], v[96:97], s[12:13], v[54:55] op_sel_hi:[1,0,1]
	v_pk_fma_f32 v[38:39], v[38:39], s[12:13], v[56:57] op_sel_hi:[1,0,1]
	v_pk_fma_f32 v[36:37], v[98:99], s[12:13], v[58:59] op_sel_hi:[1,0,1]
	v_pk_mov_b32 v[52:53], v[48:49], v[50:51] op_sel:[1,0]
	v_mov_b32_e32 v54, v48
	v_mov_b32_e32 v55, v51
	v_pk_mov_b32 v[56:57], v[40:41], v[42:43] op_sel:[1,0]
	v_mov_b32_e32 v58, v40
	v_mov_b32_e32 v59, v43
	s_waitcnt vmcnt(8)
	v_pk_mul_f32 v[44:45], v[44:45], v[90:91]
	v_pk_mul_f32 v[46:47], v[46:47], v[88:89]
	v_pk_add_f32 v[52:53], v[52:53], v[54:55]
	v_pk_add_f32 v[54:55], v[56:57], v[58:59]
	v_pk_fma_f32 v[44:45], v[102:103], s[12:13], v[44:45] op_sel_hi:[1,0,1]
	v_pk_fma_f32 v[46:47], v[100:101], s[12:13], v[46:47] op_sel_hi:[1,0,1]
	v_add_f32_e32 v9, v52, v53
	v_pk_add_f32 v[52:53], v[54:55], v[54:55] op_sel:[0,1] op_sel_hi:[1,0]
	v_add_f32_e32 v62, v36, v37
	v_add_f32_e32 v64, v38, v39
	v_mov_b32_e32 v81, v46
	v_mov_b32_e32 v63, v44
	v_mov_b32_e32 v65, v45
	v_add_f32_e32 v80, 0, v9
	v_mov_b32_e32 v53, v47
	v_pk_add_f32 v[56:57], v[62:63], v[64:65]
	v_pk_add_f32 v[52:53], v[80:81], v[52:53]
	s_nop 0
	v_pk_add_f32 v[52:53], v[52:53], v[56:57]
	s_nop 0
	v_add_f32_e32 v9, v52, v53
	v_mov_b32_e32 v29, v9
	s_nop 1
	v_add_f32_dpp v29, v29, v29 quad_perm:[1,0,3,2] row_mask:0xf bank_mask:0xf
	s_nop 1
	v_add_f32_dpp v29, v29, v29 quad_perm:[2,3,0,1] row_mask:0xf bank_mask:0xf
	s_nop 1
	v_add_f32_dpp v29, v29, v29 row_half_mirror row_mask:0xf bank_mask:0xf
	s_nop 1
	v_add_f32_dpp v29, v29, v29 row_mirror row_mask:0xf bank_mask:0xf
	s_nop 0
	v_readlane_b32 s44, v29, 0
	v_readlane_b32 s45, v29, 16
	v_readlane_b32 s46, v29, 32
	v_readlane_b32 s47, v29, 48
	s_nop 1
	v_mov_b32_e32 v29, s44
	v_add_f32_e32 v29, s45, v29
	v_add_f32_e32 v29, s46, v29
	v_add_f32_e32 v29, s47, v29
	s_nop 1
	v_accvgpr_read_b32 v52, a8
	v_accvgpr_read_b32 v53, a9
	v_accvgpr_read_b32 v54, a10
	v_accvgpr_read_b32 v55, a11
	s_nop 1
	v_accvgpr_read_b32 v56, a12
	v_accvgpr_read_b32 v57, a13
	v_accvgpr_read_b32 v58, a14
	v_accvgpr_read_b32 v59, a15
	v_mov_b32_e32 v9, v29
	v_fmamk_f32 v49, v9, 0xba800000, v49
	v_fmac_f32_e32 v48, 0xba800000, v9
	v_fmamk_f32 v51, v9, 0xba800000, v51
	v_fmac_f32_e32 v50, 0xba800000, v9
	v_fmamk_f32 v41, v9, 0xba800000, v41
	v_fmac_f32_e32 v40, 0xba800000, v9
	v_fmamk_f32 v43, v9, 0xba800000, v43
	v_fmac_f32_e32 v42, 0xba800000, v9
	v_pk_mul_f32 v[62:63], v[50:51], v[50:51]
	v_pk_mul_f32 v[64:65], v[48:49], v[48:49]
	v_pk_mul_f32 v[80:81], v[42:43], v[42:43]
	v_pk_mul_f32 v[82:83], v[40:41], v[40:41]
	v_fmac_f32_e32 v36, 0xba800000, v9
	v_fmac_f32_e32 v38, 0xba800000, v9
	v_pk_mov_b32 v[86:87], v[64:65], v[62:63] op_sel:[1,0]
	v_mov_b32_e32 v65, v63
	v_pk_mov_b32 v[62:63], v[82:83], v[80:81] op_sel:[1,0]
	v_mov_b32_e32 v83, v81
	v_fmamk_f32 v37, v9, 0xba800000, v37
	v_fmamk_f32 v39, v9, 0xba800000, v39
	v_mul_f32_e32 v60, v36, v36
	v_mul_f32_e32 v84, v38, v38
	v_pk_add_f32 v[64:65], v[86:87], v[64:65]
	v_pk_add_f32 v[62:63], v[62:63], v[82:83]
	v_fmamk_f32 v45, v9, 0xba800000, v45
	v_fmac_f32_e32 v44, 0xba800000, v9
	v_fmamk_f32 v47, v9, 0xba800000, v47
	v_fmac_f32_e32 v46, 0xba800000, v9
	v_pk_fma_f32 v[80:81], v[36:37], v[36:37], v[60:61] op_sel_hi:[1,1,0]
	v_pk_fma_f32 v[84:85], v[38:39], v[38:39], v[84:85] op_sel_hi:[1,1,0]
	v_pk_add_f32 v[64:65], v[64:65], v[64:65] op_sel_hi:[0,1]
	v_pk_add_f32 v[62:63], v[62:63], v[62:63] op_sel_hi:[0,1]
	v_mul_f32_e32 v80, v46, v46
	v_mul_f32_e32 v84, v47, v47
	v_mul_f32_e32 v64, v44, v44
	v_mul_f32_e32 v62, v45, v45
	v_pk_add_f32 v[80:81], v[80:81], v[84:85]
	v_pk_add_f32 v[62:63], v[64:65], v[62:63]
	s_nop 0
	v_pk_add_f32 v[62:63], v[80:81], v[62:63]
	s_nop 0
	v_add_f32_e32 v9, v62, v63
	v_mov_b32_e32 v29, v9
	s_nop 1
	v_add_f32_dpp v29, v29, v29 quad_perm:[1,0,3,2] row_mask:0xf bank_mask:0xf
	s_nop 1
	v_add_f32_dpp v29, v29, v29 quad_perm:[2,3,0,1] row_mask:0xf bank_mask:0xf
	s_nop 1
	v_add_f32_dpp v29, v29, v29 row_half_mirror row_mask:0xf bank_mask:0xf
	s_nop 1
	v_add_f32_dpp v29, v29, v29 row_mirror row_mask:0xf bank_mask:0xf
	s_nop 0
	v_readlane_b32 s44, v29, 0
	v_readlane_b32 s45, v29, 16
	v_readlane_b32 s46, v29, 32
	v_readlane_b32 s47, v29, 48
	s_nop 1
	v_mov_b32_e32 v29, s44
	v_add_f32_e32 v29, s45, v29
	v_add_f32_e32 v29, s46, v29
	v_add_f32_e32 v29, s47, v29
	v_mov_b32_e32 v9, v29
	v_fmamk_f32 v9, v9, 0x3a800000, v71
	v_mul_f32_e32 v29, 0x4b800000, v9
	v_cmp_gt_f32_e32 vcc, s23, v9
	s_nop 1
	v_cndmask_b32_e32 v9, v9, v29, vcc
	v_rsq_f32_e32 v29, v9
	v_ashrrev_i32_e32 v9, 31, v8
	v_lshlrev_b64 v[8:9], 12, v[8:9]
	v_lshl_add_u64 v[62:63], v[26:27], 0, v[8:9]
	v_mul_f32_e32 v8, 0x45800000, v29
	v_cndmask_b32_e32 v8, v29, v8, vcc
	v_pk_mul_f32 v[48:49], v[48:49], v[8:9] op_sel_hi:[1,0]
	v_pk_mul_f32 v[50:51], v[50:51], v[8:9] op_sel_hi:[1,0]
	v_pk_fma_f32 v[48:49], v[52:53], v[48:49], v[56:57]
	v_pk_fma_f32 v[50:51], v[54:55], v[50:51], v[58:59]
	global_store_dwordx4 v[62:63], v[48:51], off
	s_nop 1
	v_accvgpr_read_b32 v48, a16
	v_accvgpr_read_b32 v49, a17
	v_accvgpr_read_b32 v50, a18
	v_accvgpr_read_b32 v51, a19
	s_nop 0
	s_nop 1
	v_accvgpr_read_b32 v52, a20
	v_accvgpr_read_b32 v53, a21
	v_accvgpr_read_b32 v54, a22
	v_accvgpr_read_b32 v55, a23
	v_pk_mul_f32 v[42:43], v[42:43], v[8:9] op_sel_hi:[1,0]
	v_pk_mul_f32 v[40:41], v[40:41], v[8:9] op_sel_hi:[1,0]
	v_pk_mul_f32 v[38:39], v[38:39], v[8:9] op_sel_hi:[1,0]
	v_pk_mul_f32 v[36:37], v[36:37], v[8:9] op_sel_hi:[1,0]
	v_mov_b32_e32 v9, v35
	v_pk_mul_f32 v[56:57], v[44:45], v[8:9] op_sel_hi:[1,0]
	v_pk_mul_f32 v[44:45], v[46:47], v[8:9] op_sel_hi:[1,0]
	v_mov_b32_e32 v8, v34
	v_pk_fma_f32 v[40:41], v[48:49], v[40:41], v[52:53]
	v_pk_fma_f32 v[42:43], v[50:51], v[42:43], v[54:55]
	global_store_dwordx4 v[62:63], v[40:43], off offset:1024
	s_nop 1
	v_accvgpr_read_b32 v40, a24
	v_accvgpr_read_b32 v41, a25
	v_accvgpr_read_b32 v42, a26
	v_accvgpr_read_b32 v43, a27
	s_nop 0
	s_nop 1
	v_accvgpr_read_b32 v48, a28
	v_accvgpr_read_b32 v49, a29
	v_accvgpr_read_b32 v50, a30
	v_accvgpr_read_b32 v51, a31
	v_pk_fma_f32 v[36:37], v[40:41], v[36:37], v[48:49]
	v_pk_fma_f32 v[38:39], v[42:43], v[38:39], v[50:51]
	global_store_dwordx4 v[62:63], v[36:39], off offset:2048
	s_nop 1
	v_accvgpr_read_b32 v48, a32
	v_accvgpr_read_b32 v49, a33
	v_accvgpr_read_b32 v50, a34
	v_accvgpr_read_b32 v51, a35
	s_nop 1
	v_accvgpr_read_b32 v52, a36
	v_accvgpr_read_b32 v53, a37
	v_accvgpr_read_b32 v54, a38
	v_accvgpr_read_b32 v55, a39
	v_mov_b64_e32 v[42:43], v[72:73]
	v_mov_b64_e32 v[40:41], v[74:75]
	v_mov_b64_e32 v[38:39], v[76:77]
	v_mov_b64_e32 v[36:37], v[78:79]
	v_pk_fma_f32 v[44:45], v[48:49], v[44:45], v[52:53]
	v_pk_fma_f32 v[46:47], v[50:51], v[56:57], v[54:55]
	global_store_dwordx4 v[62:63], v[44:47], off offset:3072
	s_andn2_b64 exec, exec, s[8:9]
	s_cbranch_execz .LBB0_1656

.LBB0_1653:
	s_or_b64 exec, exec, s[14:15]
	s_cmp_eq_u64 s[0:1], 0
	s_cbranch_scc1 .Llf18_w4
	s_waitcnt vmcnt(9)
	s_branch .Llf18_wd
.Llf18_w4:
	s_waitcnt vmcnt(4)
.Llf18_wd:
	v_mov_b32_e32 v44, 0
	v_mov_b32_e32 v45, 0
	v_mov_b32_e32 v46, 0
	v_mov_b32_e32 v47, 0
	v_mov_b32_e32 v48, 0
	v_mov_b32_e32 v49, 0
	v_mov_b32_e32 v50, 0
	v_mov_b32_e32 v51, 0
	v_mov_b32_e32 v52, 0
	v_mov_b32_e32 v53, 0
	v_mov_b32_e32 v54, 0
	v_mov_b32_e32 v55, 0
	v_mov_b32_e32 v56, 0
	v_mov_b32_e32 v57, 0
	v_mov_b32_e32 v58, 0
	v_mov_b32_e32 v59, 0
	s_cmp_eq_u32 s43, 0
	s_cbranch_scc1 .Llf18_nopf
	v_mov_b32_e32 v60, s42
	v_lshlrev_b32_e32 v80, 16, v108
	v_and_b32_e32 v81, 0xffff0000, v108
	v_lshlrev_b32_e32 v82, 16, v109
	v_and_b32_e32 v83, 0xffff0000, v109
	v_lshlrev_b32_e32 v84, 16, v110
	v_and_b32_e32 v85, 0xffff0000, v110
	v_lshlrev_b32_e32 v86, 16, v111
	v_and_b32_e32 v87, 0xffff0000, v111
	v_pk_fma_f32 v[56:57], v[60:61], v[84:85], v[80:81] op_sel_hi:[0,1,1]
	v_pk_fma_f32 v[58:59], v[60:61], v[86:87], v[82:83] op_sel_hi:[0,1,1]
	v_lshlrev_b32_e32 v80, 16, v112
	v_and_b32_e32 v81, 0xffff0000, v112
	v_lshlrev_b32_e32 v82, 16, v113
	v_and_b32_e32 v83, 0xffff0000, v113
	v_lshlrev_b32_e32 v84, 16, v114
	v_and_b32_e32 v85, 0xffff0000, v114
	v_lshlrev_b32_e32 v86, 16, v115
	v_and_b32_e32 v87, 0xffff0000, v115
	v_pk_fma_f32 v[52:53], v[60:61], v[84:85], v[80:81] op_sel_hi:[0,1,1]
	v_pk_fma_f32 v[54:55], v[60:61], v[86:87], v[82:83] op_sel_hi:[0,1,1]
	v_lshlrev_b32_e32 v80, 16, v116
	v_and_b32_e32 v81, 0xffff0000, v116
	v_lshlrev_b32_e32 v82, 16, v117
	v_and_b32_e32 v83, 0xffff0000, v117
	v_lshlrev_b32_e32 v84, 16, v118
	v_and_b32_e32 v85, 0xffff0000, v118
	v_lshlrev_b32_e32 v86, 16, v119
	v_and_b32_e32 v87, 0xffff0000, v119
	v_pk_fma_f32 v[48:49], v[60:61], v[84:85], v[80:81] op_sel_hi:[0,1,1]
	v_pk_fma_f32 v[50:51], v[60:61], v[86:87], v[82:83] op_sel_hi:[0,1,1]
	v_lshlrev_b32_e32 v80, 16, v120
	v_and_b32_e32 v81, 0xffff0000, v120
	v_lshlrev_b32_e32 v82, 16, v121
	v_and_b32_e32 v83, 0xffff0000, v121
	v_lshlrev_b32_e32 v84, 16, v122
	v_and_b32_e32 v85, 0xffff0000, v122
	v_lshlrev_b32_e32 v86, 16, v123
	v_and_b32_e32 v87, 0xffff0000, v123
	v_pk_fma_f32 v[46:47], v[60:61], v[84:85], v[80:81] op_sel_hi:[0,1,1]
	v_pk_fma_f32 v[44:45], v[60:61], v[86:87], v[82:83] op_sel_hi:[0,1,1]
.Llf18_nopf:
	s_cmp_eq_u64 s[40:41], 0
	v_cmp_lt_i32_e64 s[0:1], s21, v8
	s_cbranch_scc1 .LBB0_1650
	s_mov_b64 s[14:15], s[40:41]
